# Hyena filter normalisation: four wave sums via DPP row adds + v_readlane (replaces 24 serialized ds_bpermute rounds per item), one b128 partial store
# speedup vs baseline: 1.0040x; 1.0040x over previous
; __device__ __forceinline__ void hy_conv_item(const Ctx& C, int l, int c) {
;     ...
;     for (int k = 0; k < 8; ++k) { const int t = tid + NTHR * k; const f32x4* hr = (const f32x4*)(hdn + (size_t)t * 64);
;         float a0 = 0.f, a1 = 0.f, a2 = 0.f, a3 = 0.f;
; #pragma unroll 1
;         for (int j8 = 0; j8 < 16; j8 += 8) {
;         f32x4 hrow[8];
; #pragma unroll
;         for (int j4 = 0; j4 < 8; ++j4) hrow[j4] = hr[j8 + j4];
; #pragma unroll
;         for (int jj4 = 0; jj4 < 8; ++jj4) { const f32x4 hv = hrow[jj4]; const int j4 = j8 + jj4;
;             const f32x4 q0 = *(const f32x4*)(w3s + 4 * j4), q1 = *(const f32x4*)(w3s + 64 + 4 * j4), q2 = *(const f32x4*)(w3s + 128 + 4 * j4), q3 = *(const f32x4*)(w3s + 192 + 4 * j4);
;             a0 += hv.x * q0.x + hv.y * q0.y + hv.z * q0.z + hv.w * q0.w; a1 += hv.x * q1.x + hv.y * q1.y + hv.z * q1.z + hv.w * q1.w;
;             a2 += hv.x * q2.x + hv.y * q2.y + hv.z * q2.z + hv.w * q2.w; a3 += hv.x * q3.x + hv.y * q3.y + hv.z * q3.z + hv.w * q3.w; } }
.LBB0_612:
	v_lshl_add_u32 v8, s7, 9, v114
	v_ashrrev_i32_e32 v9, 31, v8
	v_lshlrev_b64 v[0:1], 8, v[8:9]
	v_lshl_add_u64 v[10:11], s[4:5], 0, v[0:1]
	s_mov_b64 s[0:1], -1
	s_mov_b32 s36, 0
	v_mov_b32_e32 v14, 0
	v_mov_b32_e32 v15, v17
	v_mov_b32_e32 v12, 0
	v_mov_b32_e32 v13, v17
	v_lshlrev_b32_e32 v0, 4, v8
	s_mov_b64 s[8:9], s[4:5]
	global_load_dwordx4 v[18:21], v0, s[8:9]
	s_add_u32 s8, s8, 0x10000
	s_addc_u32 s9, s9, 0
	global_load_dwordx4 v[22:25], v0, s[8:9]
	s_add_u32 s8, s8, 0x10000
	s_addc_u32 s9, s9, 0
	global_load_dwordx4 v[26:29], v0, s[8:9]
	s_add_u32 s8, s8, 0x10000
	s_addc_u32 s9, s9, 0
	global_load_dwordx4 v[30:33], v0, s[8:9]
	s_add_u32 s8, s8, 0x10000
	s_addc_u32 s9, s9, 0
	global_load_dwordx4 v[34:37], v0, s[8:9]
	s_add_u32 s8, s8, 0x10000
	s_addc_u32 s9, s9, 0
	global_load_dwordx4 v[38:41], v0, s[8:9]
	s_add_u32 s8, s8, 0x10000
	s_addc_u32 s9, s9, 0
	global_load_dwordx4 v[42:45], v0, s[8:9]
	s_add_u32 s8, s8, 0x10000
	s_addc_u32 s9, s9, 0
	global_load_dwordx4 v[46:49], v0, s[8:9]
	s_add_u32 s8, s8, 0x10000
	s_addc_u32 s9, s9, 0
	global_load_dwordx4 v[192:195], v0, s[8:9]
	s_add_u32 s8, s8, 0x10000
	s_addc_u32 s9, s9, 0
	global_load_dwordx4 v[196:199], v0, s[8:9]
	s_add_u32 s8, s8, 0x10000
	s_addc_u32 s9, s9, 0
	global_load_dwordx4 v[200:203], v0, s[8:9]
	s_add_u32 s8, s8, 0x10000
	s_addc_u32 s9, s9, 0
	global_load_dwordx4 v[204:207], v0, s[8:9]
	s_add_u32 s8, s8, 0x10000
	s_addc_u32 s9, s9, 0
	global_load_dwordx4 v[208:211], v0, s[8:9]
	s_add_u32 s8, s8, 0x10000
	s_addc_u32 s9, s9, 0
	global_load_dwordx4 v[212:215], v0, s[8:9]
	s_add_u32 s8, s8, 0x10000
	s_addc_u32 s9, s9, 0
	global_load_dwordx4 v[228:231], v0, s[8:9]
	s_add_u32 s8, s8, 0x10000
	s_addc_u32 s9, s9, 0
	global_load_dwordx4 v[232:235], v0, s[8:9]
	v_mov_b32_e32 v9, s61
	ds_read_b128 v[142:145], v9
	ds_read_b128 v[146:149], v9 offset:16
	ds_read_b128 v[150:153], v9 offset:32
	ds_read_b128 v[154:157], v9 offset:48
	ds_read_b128 v[158:161], v9 offset:64
	ds_read_b128 v[162:165], v9 offset:80
	ds_read_b128 v[166:169], v9 offset:96
	ds_read_b128 v[170:173], v9 offset:112
	ds_read_b128 v[174:177], v9 offset:128
	ds_read_b128 v[178:181], v9 offset:144
	ds_read_b128 v[50:53], v9 offset:160
	ds_read_b128 v[54:57], v9 offset:176
	s_waitcnt vmcnt(15) lgkmcnt(11)
	v_pk_fma_f32 v[14:15], v[18:19], v[142:143], v[14:15] op_sel_hi:[0,1,1]
	v_pk_fma_f32 v[12:13], v[18:19], v[144:145], v[12:13] op_sel_hi:[0,1,1]
	ds_read_b128 v[142:145], v9 offset:192
	s_waitcnt lgkmcnt(11)
	v_pk_mul_f32 v[58:59], v[18:19], v[146:147] op_sel:[1,0] op_sel_hi:[1,1]
	v_pk_mul_f32 v[60:61], v[18:19], v[148:149] op_sel:[1,0] op_sel_hi:[1,1]
	ds_read_b128 v[146:149], v9 offset:208
	s_waitcnt lgkmcnt(11)
	v_pk_fma_f32 v[14:15], v[20:21], v[150:151], v[14:15] op_sel_hi:[0,1,1]
	v_pk_fma_f32 v[12:13], v[20:21], v[152:153], v[12:13] op_sel_hi:[0,1,1]
	ds_read_b128 v[150:153], v9 offset:224
	s_waitcnt lgkmcnt(11)
	v_pk_fma_f32 v[58:59], v[20:21], v[154:155], v[58:59] op_sel:[1,0,0] op_sel_hi:[1,1,1]
	v_pk_fma_f32 v[60:61], v[20:21], v[156:157], v[60:61] op_sel:[1,0,0] op_sel_hi:[1,1,1]
	ds_read_b128 v[154:157], v9 offset:240
	s_waitcnt vmcnt(14) lgkmcnt(11)
	v_pk_fma_f32 v[14:15], v[22:23], v[158:159], v[14:15] op_sel_hi:[0,1,1]
	v_pk_fma_f32 v[12:13], v[22:23], v[160:161], v[12:13] op_sel_hi:[0,1,1]
	ds_read_b128 v[158:161], v9 offset:256
	s_waitcnt lgkmcnt(11)
	v_pk_fma_f32 v[58:59], v[22:23], v[162:163], v[58:59] op_sel:[1,0,0] op_sel_hi:[1,1,1]
	v_pk_fma_f32 v[60:61], v[22:23], v[164:165], v[60:61] op_sel:[1,0,0] op_sel_hi:[1,1,1]
	ds_read_b128 v[162:165], v9 offset:272
	s_waitcnt lgkmcnt(11)
	v_pk_fma_f32 v[14:15], v[24:25], v[166:167], v[14:15] op_sel_hi:[0,1,1]
	v_pk_fma_f32 v[12:13], v[24:25], v[168:169], v[12:13] op_sel_hi:[0,1,1]
	ds_read_b128 v[166:169], v9 offset:288
	s_waitcnt lgkmcnt(11)
	v_pk_fma_f32 v[58:59], v[24:25], v[170:171], v[58:59] op_sel:[1,0,0] op_sel_hi:[1,1,1]
	v_pk_fma_f32 v[60:61], v[24:25], v[172:173], v[60:61] op_sel:[1,0,0] op_sel_hi:[1,1,1]
	ds_read_b128 v[170:173], v9 offset:304
	s_waitcnt vmcnt(13) lgkmcnt(11)
	v_pk_fma_f32 v[14:15], v[26:27], v[174:175], v[14:15] op_sel_hi:[0,1,1]
	v_pk_fma_f32 v[12:13], v[26:27], v[176:177], v[12:13] op_sel_hi:[0,1,1]
	ds_read_b128 v[174:177], v9 offset:320
	s_waitcnt lgkmcnt(11)
	v_pk_fma_f32 v[58:59], v[26:27], v[178:179], v[58:59] op_sel:[1,0,0] op_sel_hi:[1,1,1]
	v_pk_fma_f32 v[60:61], v[26:27], v[180:181], v[60:61] op_sel:[1,0,0] op_sel_hi:[1,1,1]
	ds_read_b128 v[178:181], v9 offset:336
	s_waitcnt lgkmcnt(11)
	v_pk_fma_f32 v[14:15], v[28:29], v[50:51], v[14:15] op_sel_hi:[0,1,1]
	v_pk_fma_f32 v[12:13], v[28:29], v[52:53], v[12:13] op_sel_hi:[0,1,1]
	ds_read_b128 v[50:53], v9 offset:352
	s_waitcnt lgkmcnt(11)
	v_pk_fma_f32 v[58:59], v[28:29], v[54:55], v[58:59] op_sel:[1,0,0] op_sel_hi:[1,1,1]
	v_pk_fma_f32 v[60:61], v[28:29], v[56:57], v[60:61] op_sel:[1,0,0] op_sel_hi:[1,1,1]
	ds_read_b128 v[54:57], v9 offset:368
	s_waitcnt vmcnt(12) lgkmcnt(11)
	v_pk_fma_f32 v[14:15], v[30:31], v[142:143], v[14:15] op_sel_hi:[0,1,1]
	v_pk_fma_f32 v[12:13], v[30:31], v[144:145], v[12:13] op_sel_hi:[0,1,1]
	ds_read_b128 v[142:145], v9 offset:384
	s_waitcnt lgkmcnt(11)
	v_pk_fma_f32 v[58:59], v[30:31], v[146:147], v[58:59] op_sel:[1,0,0] op_sel_hi:[1,1,1]
	v_pk_fma_f32 v[60:61], v[30:31], v[148:149], v[60:61] op_sel:[1,0,0] op_sel_hi:[1,1,1]
	ds_read_b128 v[146:149], v9 offset:400
	s_waitcnt lgkmcnt(11)
	v_pk_fma_f32 v[14:15], v[32:33], v[150:151], v[14:15] op_sel_hi:[0,1,1]
	v_pk_fma_f32 v[12:13], v[32:33], v[152:153], v[12:13] op_sel_hi:[0,1,1]
	ds_read_b128 v[150:153], v9 offset:416
	s_waitcnt lgkmcnt(11)
; __device__ __forceinline__ void hy_conv_item(const Ctx& C, int l, int c) {
;     ...
;         for (int jj4 = 0; jj4 < 8; ++jj4) { const f32x4 hv = hrow[jj4]; const int j4 = j8 + jj4;
;             const f32x4 q0 = *(const f32x4*)(w3s + 4 * j4), q1 = *(const f32x4*)(w3s + 64 + 4 * j4), q2 = *(const f32x4*)(w3s + 128 + 4 * j4), q3 = *(const f32x4*)(w3s + 192 + 4 * j4);
;             a0 += hv.x * q0.x + hv.y * q0.y + hv.z * q0.z + hv.w * q0.w; a1 += hv.x * q1.x + hv.y * q1.y + hv.z * q1.z + hv.w * q1.w;
;             a2 += hv.x * q2.x + hv.y * q2.y + hv.z * q2.z + hv.w * q2.w; a3 += hv.x * q3.x + hv.y * q3.y + hv.z * q3.z + hv.w * q3.w; } }
	v_pk_fma_f32 v[58:59], v[32:33], v[154:155], v[58:59] op_sel:[1,0,0] op_sel_hi:[1,1,1]
	v_pk_fma_f32 v[60:61], v[32:33], v[156:157], v[60:61] op_sel:[1,0,0] op_sel_hi:[1,1,1]
	ds_read_b128 v[154:157], v9 offset:432
	s_waitcnt vmcnt(11) lgkmcnt(11)
	v_pk_fma_f32 v[14:15], v[34:35], v[158:159], v[14:15] op_sel_hi:[0,1,1]
	v_pk_fma_f32 v[12:13], v[34:35], v[160:161], v[12:13] op_sel_hi:[0,1,1]
	ds_read_b128 v[158:161], v9 offset:448
	s_waitcnt lgkmcnt(11)
	v_pk_fma_f32 v[58:59], v[34:35], v[162:163], v[58:59] op_sel:[1,0,0] op_sel_hi:[1,1,1]
	v_pk_fma_f32 v[60:61], v[34:35], v[164:165], v[60:61] op_sel:[1,0,0] op_sel_hi:[1,1,1]
	ds_read_b128 v[162:165], v9 offset:464
	s_waitcnt lgkmcnt(11)
	v_pk_fma_f32 v[14:15], v[36:37], v[166:167], v[14:15] op_sel_hi:[0,1,1]
	v_pk_fma_f32 v[12:13], v[36:37], v[168:169], v[12:13] op_sel_hi:[0,1,1]
	ds_read_b128 v[166:169], v9 offset:480
	s_waitcnt lgkmcnt(11)
	v_pk_fma_f32 v[58:59], v[36:37], v[170:171], v[58:59] op_sel:[1,0,0] op_sel_hi:[1,1,1]
	v_pk_fma_f32 v[60:61], v[36:37], v[172:173], v[60:61] op_sel:[1,0,0] op_sel_hi:[1,1,1]
	ds_read_b128 v[170:173], v9 offset:496
	s_waitcnt vmcnt(10) lgkmcnt(11)
	v_pk_fma_f32 v[14:15], v[38:39], v[174:175], v[14:15] op_sel_hi:[0,1,1]
	v_pk_fma_f32 v[12:13], v[38:39], v[176:177], v[12:13] op_sel_hi:[0,1,1]
	ds_read_b128 v[174:177], v9 offset:512
	s_waitcnt lgkmcnt(11)
	v_pk_fma_f32 v[58:59], v[38:39], v[178:179], v[58:59] op_sel:[1,0,0] op_sel_hi:[1,1,1]
	v_pk_fma_f32 v[60:61], v[38:39], v[180:181], v[60:61] op_sel:[1,0,0] op_sel_hi:[1,1,1]
	ds_read_b128 v[178:181], v9 offset:528
	s_waitcnt lgkmcnt(11)
	v_pk_fma_f32 v[14:15], v[40:41], v[50:51], v[14:15] op_sel_hi:[0,1,1]
	v_pk_fma_f32 v[12:13], v[40:41], v[52:53], v[12:13] op_sel_hi:[0,1,1]
	ds_read_b128 v[50:53], v9 offset:544
	s_waitcnt lgkmcnt(11)
	v_pk_fma_f32 v[58:59], v[40:41], v[54:55], v[58:59] op_sel:[1,0,0] op_sel_hi:[1,1,1]
	v_pk_fma_f32 v[60:61], v[40:41], v[56:57], v[60:61] op_sel:[1,0,0] op_sel_hi:[1,1,1]
	ds_read_b128 v[54:57], v9 offset:560
	s_waitcnt vmcnt(9) lgkmcnt(11)
	v_pk_fma_f32 v[14:15], v[42:43], v[142:143], v[14:15] op_sel_hi:[0,1,1]
	v_pk_fma_f32 v[12:13], v[42:43], v[144:145], v[12:13] op_sel_hi:[0,1,1]
	ds_read_b128 v[142:145], v9 offset:576
	s_waitcnt lgkmcnt(11)
	v_pk_fma_f32 v[58:59], v[42:43], v[146:147], v[58:59] op_sel:[1,0,0] op_sel_hi:[1,1,1]
	v_pk_fma_f32 v[60:61], v[42:43], v[148:149], v[60:61] op_sel:[1,0,0] op_sel_hi:[1,1,1]
	ds_read_b128 v[146:149], v9 offset:592
	s_waitcnt lgkmcnt(11)
	v_pk_fma_f32 v[14:15], v[44:45], v[150:151], v[14:15] op_sel_hi:[0,1,1]
	v_pk_fma_f32 v[12:13], v[44:45], v[152:153], v[12:13] op_sel_hi:[0,1,1]
	ds_read_b128 v[150:153], v9 offset:608
	s_waitcnt lgkmcnt(11)
	v_pk_fma_f32 v[58:59], v[44:45], v[154:155], v[58:59] op_sel:[1,0,0] op_sel_hi:[1,1,1]
	v_pk_fma_f32 v[60:61], v[44:45], v[156:157], v[60:61] op_sel:[1,0,0] op_sel_hi:[1,1,1]
	ds_read_b128 v[154:157], v9 offset:624
	s_waitcnt vmcnt(8) lgkmcnt(11)
	v_pk_fma_f32 v[14:15], v[46:47], v[158:159], v[14:15] op_sel_hi:[0,1,1]
	v_pk_fma_f32 v[12:13], v[46:47], v[160:161], v[12:13] op_sel_hi:[0,1,1]
	ds_read_b128 v[158:161], v9 offset:640
	s_waitcnt lgkmcnt(11)
	v_pk_fma_f32 v[58:59], v[46:47], v[162:163], v[58:59] op_sel:[1,0,0] op_sel_hi:[1,1,1]
	v_pk_fma_f32 v[60:61], v[46:47], v[164:165], v[60:61] op_sel:[1,0,0] op_sel_hi:[1,1,1]
	ds_read_b128 v[162:165], v9 offset:656
	s_waitcnt lgkmcnt(11)
	v_pk_fma_f32 v[14:15], v[48:49], v[166:167], v[14:15] op_sel_hi:[0,1,1]
	v_pk_fma_f32 v[12:13], v[48:49], v[168:169], v[12:13] op_sel_hi:[0,1,1]
	ds_read_b128 v[166:169], v9 offset:672
	s_waitcnt lgkmcnt(11)
	v_pk_fma_f32 v[58:59], v[48:49], v[170:171], v[58:59] op_sel:[1,0,0] op_sel_hi:[1,1,1]
	v_pk_fma_f32 v[60:61], v[48:49], v[172:173], v[60:61] op_sel:[1,0,0] op_sel_hi:[1,1,1]
	ds_read_b128 v[170:173], v9 offset:688
	s_waitcnt vmcnt(7) lgkmcnt(11)
	v_pk_fma_f32 v[14:15], v[192:193], v[174:175], v[14:15] op_sel_hi:[0,1,1]
	v_pk_fma_f32 v[12:13], v[192:193], v[176:177], v[12:13] op_sel_hi:[0,1,1]
	ds_read_b128 v[174:177], v9 offset:704
	s_waitcnt lgkmcnt(11)
	v_pk_fma_f32 v[58:59], v[192:193], v[178:179], v[58:59] op_sel:[1,0,0] op_sel_hi:[1,1,1]
	v_pk_fma_f32 v[60:61], v[192:193], v[180:181], v[60:61] op_sel:[1,0,0] op_sel_hi:[1,1,1]
	ds_read_b128 v[178:181], v9 offset:720
	s_waitcnt lgkmcnt(11)
	v_pk_fma_f32 v[14:15], v[194:195], v[50:51], v[14:15] op_sel_hi:[0,1,1]
	v_pk_fma_f32 v[12:13], v[194:195], v[52:53], v[12:13] op_sel_hi:[0,1,1]
	ds_read_b128 v[50:53], v9 offset:736
	s_waitcnt lgkmcnt(11)
	v_pk_fma_f32 v[58:59], v[194:195], v[54:55], v[58:59] op_sel:[1,0,0] op_sel_hi:[1,1,1]
	v_pk_fma_f32 v[60:61], v[194:195], v[56:57], v[60:61] op_sel:[1,0,0] op_sel_hi:[1,1,1]
	ds_read_b128 v[54:57], v9 offset:752
	s_waitcnt vmcnt(6) lgkmcnt(11)
	v_pk_fma_f32 v[14:15], v[196:197], v[142:143], v[14:15] op_sel_hi:[0,1,1]
	v_pk_fma_f32 v[12:13], v[196:197], v[144:145], v[12:13] op_sel_hi:[0,1,1]
	ds_read_b128 v[142:145], v9 offset:768
	s_waitcnt lgkmcnt(11)
	v_pk_fma_f32 v[58:59], v[196:197], v[146:147], v[58:59] op_sel:[1,0,0] op_sel_hi:[1,1,1]
	v_pk_fma_f32 v[60:61], v[196:197], v[148:149], v[60:61] op_sel:[1,0,0] op_sel_hi:[1,1,1]
	ds_read_b128 v[146:149], v9 offset:784
	s_waitcnt lgkmcnt(11)
	v_pk_fma_f32 v[14:15], v[198:199], v[150:151], v[14:15] op_sel_hi:[0,1,1]
	v_pk_fma_f32 v[12:13], v[198:199], v[152:153], v[12:13] op_sel_hi:[0,1,1]
	ds_read_b128 v[150:153], v9 offset:800
	s_waitcnt lgkmcnt(11)
	v_pk_fma_f32 v[58:59], v[198:199], v[154:155], v[58:59] op_sel:[1,0,0] op_sel_hi:[1,1,1]
	v_pk_fma_f32 v[60:61], v[198:199], v[156:157], v[60:61] op_sel:[1,0,0] op_sel_hi:[1,1,1]
	ds_read_b128 v[154:157], v9 offset:816
	s_waitcnt vmcnt(5) lgkmcnt(11)
; __device__ __forceinline__ void hy_conv_item(const Ctx& C, int l, int c) {
;     ...
;         for (int jj4 = 0; jj4 < 8; ++jj4) { const f32x4 hv = hrow[jj4]; const int j4 = j8 + jj4;
;             const f32x4 q0 = *(const f32x4*)(w3s + 4 * j4), q1 = *(const f32x4*)(w3s + 64 + 4 * j4), q2 = *(const f32x4*)(w3s + 128 + 4 * j4), q3 = *(const f32x4*)(w3s + 192 + 4 * j4);
;             a0 += hv.x * q0.x + hv.y * q0.y + hv.z * q0.z + hv.w * q0.w; a1 += hv.x * q1.x + hv.y * q1.y + hv.z * q1.z + hv.w * q1.w;
;             a2 += hv.x * q2.x + hv.y * q2.y + hv.z * q2.z + hv.w * q2.w; a3 += hv.x * q3.x + hv.y * q3.y + hv.z * q3.z + hv.w * q3.w; } }
;         const float dec = __expf(-((float)t / 4095.f) * adelta);
;         a0 *= dec; a1 *= dec; a2 *= dec; a3 *= dec;
;         hft[t] = a0; hft[4096 + t] = a1; hft[8192 + t] = a2; hft[12288 + t] = a3;
;         ss[0] += a0 * a0; ss[1] += a1 * a1; ss[2] += a2 * a2; ss[3] += a3 * a3; }
	v_pk_fma_f32 v[14:15], v[200:201], v[158:159], v[14:15] op_sel_hi:[0,1,1]
	v_pk_fma_f32 v[12:13], v[200:201], v[160:161], v[12:13] op_sel_hi:[0,1,1]
	ds_read_b128 v[158:161], v9 offset:832
	s_waitcnt lgkmcnt(11)
	v_pk_fma_f32 v[58:59], v[200:201], v[162:163], v[58:59] op_sel:[1,0,0] op_sel_hi:[1,1,1]
	v_pk_fma_f32 v[60:61], v[200:201], v[164:165], v[60:61] op_sel:[1,0,0] op_sel_hi:[1,1,1]
	ds_read_b128 v[162:165], v9 offset:848
	s_waitcnt lgkmcnt(11)
	v_pk_fma_f32 v[14:15], v[202:203], v[166:167], v[14:15] op_sel_hi:[0,1,1]
	v_pk_fma_f32 v[12:13], v[202:203], v[168:169], v[12:13] op_sel_hi:[0,1,1]
	ds_read_b128 v[166:169], v9 offset:864
	s_waitcnt lgkmcnt(11)
	v_pk_fma_f32 v[58:59], v[202:203], v[170:171], v[58:59] op_sel:[1,0,0] op_sel_hi:[1,1,1]
	v_pk_fma_f32 v[60:61], v[202:203], v[172:173], v[60:61] op_sel:[1,0,0] op_sel_hi:[1,1,1]
	ds_read_b128 v[170:173], v9 offset:880
	s_waitcnt vmcnt(4) lgkmcnt(11)
	v_pk_fma_f32 v[14:15], v[204:205], v[174:175], v[14:15] op_sel_hi:[0,1,1]
	v_pk_fma_f32 v[12:13], v[204:205], v[176:177], v[12:13] op_sel_hi:[0,1,1]
	ds_read_b128 v[174:177], v9 offset:896
	s_waitcnt lgkmcnt(11)
	v_pk_fma_f32 v[58:59], v[204:205], v[178:179], v[58:59] op_sel:[1,0,0] op_sel_hi:[1,1,1]
	v_pk_fma_f32 v[60:61], v[204:205], v[180:181], v[60:61] op_sel:[1,0,0] op_sel_hi:[1,1,1]
	ds_read_b128 v[178:181], v9 offset:912
	s_waitcnt lgkmcnt(11)
	v_pk_fma_f32 v[14:15], v[206:207], v[50:51], v[14:15] op_sel_hi:[0,1,1]
	v_pk_fma_f32 v[12:13], v[206:207], v[52:53], v[12:13] op_sel_hi:[0,1,1]
	ds_read_b128 v[50:53], v9 offset:928
	s_waitcnt lgkmcnt(11)
	v_pk_fma_f32 v[58:59], v[206:207], v[54:55], v[58:59] op_sel:[1,0,0] op_sel_hi:[1,1,1]
	v_pk_fma_f32 v[60:61], v[206:207], v[56:57], v[60:61] op_sel:[1,0,0] op_sel_hi:[1,1,1]
	ds_read_b128 v[54:57], v9 offset:944
	s_waitcnt vmcnt(3) lgkmcnt(11)
	v_pk_fma_f32 v[14:15], v[208:209], v[142:143], v[14:15] op_sel_hi:[0,1,1]
	v_pk_fma_f32 v[12:13], v[208:209], v[144:145], v[12:13] op_sel_hi:[0,1,1]
	ds_read_b128 v[142:145], v9 offset:960
	s_waitcnt lgkmcnt(11)
	v_pk_fma_f32 v[58:59], v[208:209], v[146:147], v[58:59] op_sel:[1,0,0] op_sel_hi:[1,1,1]
	v_pk_fma_f32 v[60:61], v[208:209], v[148:149], v[60:61] op_sel:[1,0,0] op_sel_hi:[1,1,1]
	ds_read_b128 v[146:149], v9 offset:976
	s_waitcnt lgkmcnt(11)
	v_pk_fma_f32 v[14:15], v[210:211], v[150:151], v[14:15] op_sel_hi:[0,1,1]
	v_pk_fma_f32 v[12:13], v[210:211], v[152:153], v[12:13] op_sel_hi:[0,1,1]
	ds_read_b128 v[150:153], v9 offset:992
	s_waitcnt lgkmcnt(11)
	v_pk_fma_f32 v[58:59], v[210:211], v[154:155], v[58:59] op_sel:[1,0,0] op_sel_hi:[1,1,1]
	v_pk_fma_f32 v[60:61], v[210:211], v[156:157], v[60:61] op_sel:[1,0,0] op_sel_hi:[1,1,1]
	ds_read_b128 v[154:157], v9 offset:1008
	s_waitcnt vmcnt(2) lgkmcnt(11)
	v_pk_fma_f32 v[14:15], v[212:213], v[158:159], v[14:15] op_sel_hi:[0,1,1]
	v_pk_fma_f32 v[12:13], v[212:213], v[160:161], v[12:13] op_sel_hi:[0,1,1]
	s_waitcnt lgkmcnt(10)
	v_pk_fma_f32 v[58:59], v[212:213], v[162:163], v[58:59] op_sel:[1,0,0] op_sel_hi:[1,1,1]
	v_pk_fma_f32 v[60:61], v[212:213], v[164:165], v[60:61] op_sel:[1,0,0] op_sel_hi:[1,1,1]
	s_waitcnt lgkmcnt(9)
	v_pk_fma_f32 v[14:15], v[214:215], v[166:167], v[14:15] op_sel_hi:[0,1,1]
	v_pk_fma_f32 v[12:13], v[214:215], v[168:169], v[12:13] op_sel_hi:[0,1,1]
	s_waitcnt lgkmcnt(8)
	v_pk_fma_f32 v[58:59], v[214:215], v[170:171], v[58:59] op_sel:[1,0,0] op_sel_hi:[1,1,1]
	v_pk_fma_f32 v[60:61], v[214:215], v[172:173], v[60:61] op_sel:[1,0,0] op_sel_hi:[1,1,1]
	s_waitcnt vmcnt(1) lgkmcnt(7)
	v_pk_fma_f32 v[14:15], v[228:229], v[174:175], v[14:15] op_sel_hi:[0,1,1]
	v_pk_fma_f32 v[12:13], v[228:229], v[176:177], v[12:13] op_sel_hi:[0,1,1]
	s_waitcnt lgkmcnt(6)
	v_pk_fma_f32 v[58:59], v[228:229], v[178:179], v[58:59] op_sel:[1,0,0] op_sel_hi:[1,1,1]
	v_pk_fma_f32 v[60:61], v[228:229], v[180:181], v[60:61] op_sel:[1,0,0] op_sel_hi:[1,1,1]
	s_waitcnt lgkmcnt(5)
	v_pk_fma_f32 v[14:15], v[230:231], v[50:51], v[14:15] op_sel_hi:[0,1,1]
	v_pk_fma_f32 v[12:13], v[230:231], v[52:53], v[12:13] op_sel_hi:[0,1,1]
	s_waitcnt lgkmcnt(4)
	v_pk_fma_f32 v[58:59], v[230:231], v[54:55], v[58:59] op_sel:[1,0,0] op_sel_hi:[1,1,1]
	v_pk_fma_f32 v[60:61], v[230:231], v[56:57], v[60:61] op_sel:[1,0,0] op_sel_hi:[1,1,1]
	s_waitcnt vmcnt(0) lgkmcnt(3)
	v_pk_fma_f32 v[14:15], v[232:233], v[142:143], v[14:15] op_sel_hi:[0,1,1]
	v_pk_fma_f32 v[12:13], v[232:233], v[144:145], v[12:13] op_sel_hi:[0,1,1]
	s_waitcnt lgkmcnt(2)
	v_pk_fma_f32 v[58:59], v[232:233], v[146:147], v[58:59] op_sel:[1,0,0] op_sel_hi:[1,1,1]
	v_pk_fma_f32 v[60:61], v[232:233], v[148:149], v[60:61] op_sel:[1,0,0] op_sel_hi:[1,1,1]
	s_waitcnt lgkmcnt(1)
	v_pk_fma_f32 v[14:15], v[234:235], v[150:151], v[14:15] op_sel_hi:[0,1,1]
	v_pk_fma_f32 v[12:13], v[234:235], v[152:153], v[12:13] op_sel_hi:[0,1,1]
	s_waitcnt lgkmcnt(0)
	v_pk_fma_f32 v[58:59], v[234:235], v[154:155], v[58:59] op_sel:[1,0,0] op_sel_hi:[1,1,1]
	v_pk_fma_f32 v[60:61], v[234:235], v[156:157], v[60:61] op_sel:[1,0,0] op_sel_hi:[1,1,1]
	v_pk_add_f32 v[14:15], v[14:15], v[58:59]
	v_pk_add_f32 v[12:13], v[12:13], v[60:61]
	v_cvt_f32_i32_e32 v0, v8
	s_add_i32 s7, s7, 1
	s_cmp_eq_u32 s7, 8
	v_rcp_f32_e32 v1, s22
	s_nop 0
	v_mul_f32_e32 v0, v0, v1
	v_mul_f32_e32 v0, v16, v0
	v_mul_f32_e32 v0, 0x3fb8aa3b, v0
	v_exp_f32_e32 v0, v0
	v_lshl_add_u32 v1, v8, 2, 0
	v_add_u32_e32 v8, 0x11000, v1
	v_pk_mul_f32 v[2:3], v[0:1], v[14:15] op_sel_hi:[0,1]
	v_pk_mul_f32 v[0:1], v[0:1], v[12:13] op_sel_hi:[0,1]
	v_pk_fma_f32 v[6:7], v[2:3], v[2:3], v[6:7]
	v_pk_fma_f32 v[4:5], v[0:1], v[0:1], v[4:5]
	ds_write2st64_b32 v8, v2, v3 offset1:64
	ds_write2st64_b32 v8, v0, v1 offset0:128 offset1:192
	s_cbranch_scc0 .LBB0_612
; __device__ __forceinline__ float wave_sum(float v) {
; #pragma unroll
;     for (int o = 1; o < 64; o <<= 1) v += __shfl_xor(v, o);
;     return v;
; }
; __device__ __forceinline__ void hy_conv_item(const Ctx& C, int l, int c) {
;     ...
;     for (int q = 0; q < 4; ++q) { const float s_ = wave_sum(ss[q]); if (lane == 0) red[w * 4 + q] = s_; }
	s_nop 1
	v_add_f32_dpp v6, v6, v6 quad_perm:[1,0,3,2] row_mask:0xf bank_mask:0xf
	v_add_f32_dpp v7, v7, v7 quad_perm:[1,0,3,2] row_mask:0xf bank_mask:0xf
	v_add_f32_dpp v4, v4, v4 quad_perm:[1,0,3,2] row_mask:0xf bank_mask:0xf
	v_add_f32_dpp v5, v5, v5 quad_perm:[1,0,3,2] row_mask:0xf bank_mask:0xf
	v_add_f32_dpp v6, v6, v6 quad_perm:[2,3,0,1] row_mask:0xf bank_mask:0xf
	v_add_f32_dpp v7, v7, v7 quad_perm:[2,3,0,1] row_mask:0xf bank_mask:0xf
	v_add_f32_dpp v4, v4, v4 quad_perm:[2,3,0,1] row_mask:0xf bank_mask:0xf
	v_add_f32_dpp v5, v5, v5 quad_perm:[2,3,0,1] row_mask:0xf bank_mask:0xf
	v_add_f32_dpp v6, v6, v6 row_half_mirror row_mask:0xf bank_mask:0xf
	v_add_f32_dpp v7, v7, v7 row_half_mirror row_mask:0xf bank_mask:0xf
	v_add_f32_dpp v4, v4, v4 row_half_mirror row_mask:0xf bank_mask:0xf
	v_add_f32_dpp v5, v5, v5 row_half_mirror row_mask:0xf bank_mask:0xf
	v_add_f32_dpp v6, v6, v6 row_mirror row_mask:0xf bank_mask:0xf
	v_add_f32_dpp v7, v7, v7 row_mirror row_mask:0xf bank_mask:0xf
	v_add_f32_dpp v4, v4, v4 row_mirror row_mask:0xf bank_mask:0xf
	v_add_f32_dpp v5, v5, v5 row_mirror row_mask:0xf bank_mask:0xf
	s_nop 0
	v_readlane_b32 s68, v6, 0
	v_readlane_b32 s69, v6, 16
	v_readlane_b32 s70, v6, 32
	v_readlane_b32 s71, v6, 48
	v_readlane_b32 s72, v7, 0
	v_readlane_b32 s73, v7, 16
	v_readlane_b32 s74, v7, 32
	v_readlane_b32 s75, v7, 48
	v_readlane_b32 s76, v4, 0
	v_readlane_b32 s77, v4, 16
	v_readlane_b32 s78, v4, 32
	v_readlane_b32 s79, v4, 48
	v_readlane_b32 s80, v5, 0
	v_readlane_b32 s81, v5, 16
	v_readlane_b32 s82, v5, 32
	v_readlane_b32 s83, v5, 48
	s_nop 1
	v_mov_b32_e32 v0, s68
	v_add_f32_e32 v0, s69, v0
	v_add_f32_e32 v0, s70, v0
	v_add_f32_e32 v0, s71, v0
	v_mov_b32_e32 v1, s72
	v_add_f32_e32 v1, s73, v1
	v_add_f32_e32 v1, s74, v1
	v_add_f32_e32 v1, s75, v1
	v_mov_b32_e32 v2, s76
	v_add_f32_e32 v2, s77, v2
	v_add_f32_e32 v2, s78, v2
	v_add_f32_e32 v2, s79, v2
	v_mov_b32_e32 v3, s80
	v_add_f32_e32 v3, s81, v3
	v_add_f32_e32 v3, s82, v3
	v_add_f32_e32 v3, s83, v3
	s_and_saveexec_b64 s[0:1], s[46:47]
	s_mov_b32 s10, 0x358637bd
	s_cbranch_execz .LBB0_623
	s_add_i32 s7, s12, 0x25080
	v_mov_b32_e32 v9, s7
	ds_write_b128 v9, v[0:3]
